# E34: lever 1 counted waits: explicit full vmcnt drain before the MLA staging LDS writes removed (compiler's counted waits remain), on top of E28
# speedup vs baseline: 1.0008x; 1.0008x over previous
; #define SBAR() __builtin_amdgcn_sched_barrier(0)
; #define QKT(P0, P1, KS) do { if constexpr (MI) qkt_mi<NQK>(P0, P1, KS, qr, r32, hi, minit); else qkt<NQK>(P0, P1, KS, qr, r32, hi); } while (0)
; #define DECIDE(P0, P1, MN, AL) do { if constexpr (MI) decide_mi(P0, P1, minit, Mref, AL, thr2, false); else decideSM(P0, P1, m_reg, MN, AL, C, thr); } while (0)
; template <int NQK>
; __device__ __forceinline__ void qkt(f32x16& p0, f32x16& p1, const char* Ks, const bf16x8* qr, int r32, int hi) {
;   constexpr int KROW = NQK * 32 + 16;
;   p0 = f32x16{}; p1 = f32x16{};
; #pragma unroll
;   for (int d0 = 0; d0 < NQK; ++d0) { const int cb = (d0 * 16 + hi * 8) * 2;
;     bf16x8 b0 = *reinterpret_cast<const bf16x8*>(Ks + r32 * KROW + cb);
;     bf16x8 b1 = *reinterpret_cast<const bf16x8*>(Ks + (32 + r32) * KROW + cb);
;     p0 = __builtin_amdgcn_mfma_f32_32x32x16_bf16(b0, qr[d0], p0, 0, 0, 0);
;     p1 = __builtin_amdgcn_mfma_f32_32x32x16_bf16(b1, qr[d0], p1, 0, 0, 0); }
; }
; template <int NQK, int SD, bool MI> ...
;     ...
;   for (int j = 1; j + 1 < NT; j += 2) {
;     SBAR(); QKT(pB0, pB1, K_lds + rc * KT);
;     finishSM(pA0, pA1, alA, l_reg, pa0, pa1, pa2, pa3); DECIDE(pB0, pB1, mnB, alB); SBAR();
.LBB0_2539:
	s_mov_b32 s14, s44
	s_mov_b32 s44, s8
	s_mul_i32 s8, s14, 0x6400
	v_add_u32_e32 v169, s8, v174
	ds_read_b128 v[64:67], v169 offset:61952
	ds_read_b128 v[68:71], v169 offset:49152
	ds_read_b128 v[180:183], v169 offset:49184
	ds_read_b128 v[222:225], v169 offset:61984
	v_exp_f32_e32 v231, v146
	v_add_f32_e32 v146, 0, v184
	s_waitcnt lgkmcnt(2)
	v_mfma_f32_32x32x16_bf16 v[80:95], v[68:71], v[140:143], 0
	v_add_f32_e32 v146, v185, v146
	v_add_f32_e32 v146, v189, v146
	v_add_f32_e32 v146, v191, v146
	v_add_f32_e32 v146, v198, v146
	v_add_f32_e32 v146, v200, v146
	v_add_f32_e32 v146, v214, v146
	v_add_f32_e32 v146, v217, v146
	v_mfma_f32_32x32x16_bf16 v[64:79], v[64:67], v[140:143], 0
	v_add_f32_e32 v146, v215, v146
	v_add_f32_e32 v146, v218, v146
	v_add_f32_e32 v146, v199, v146
	v_add_f32_e32 v146, v201, v146
	v_add_f32_e32 v146, v216, v146
	v_add_f32_e32 v146, v219, v146
	v_add_f32_e32 v146, v220, v146
	s_waitcnt lgkmcnt(1)
	v_mfma_f32_32x32x16_bf16 v[80:95], v[180:183], v[136:139], v[80:95]
	v_add_f32_e32 v146, v221, v146
	v_exp_f32_e32 v229, v150
	v_exp_f32_e32 v226, v155
	v_exp_f32_e32 v227, v152
	v_exp_f32_e32 v228, v153
	v_exp_f32_e32 v230, v151
	v_exp_f32_e32 v148, v148
	s_waitcnt lgkmcnt(0)
	v_mfma_f32_32x32x16_bf16 v[64:79], v[222:225], v[136:139], v[64:79]
	ds_read_b128 v[180:183], v169 offset:49216
	ds_read_b128 v[222:225], v169 offset:62016
	v_exp_f32_e32 v149, v149
	v_exp_f32_e32 v232, v147
	v_cvt_pk_bf16_f32 v155, v199, v201
	v_cvt_pk_bf16_f32 v147, v229, v230
	s_waitcnt lgkmcnt(1)
	v_mfma_f32_32x32x16_bf16 v[80:95], v[180:183], v[132:135], v[80:95]
	s_waitcnt lgkmcnt(0)
	v_mfma_f32_32x32x16_bf16 v[64:79], v[222:225], v[132:135], v[64:79]
	ds_read_b128 v[180:183], v169 offset:49248
	ds_read_b128 v[222:225], v169 offset:62048
	s_waitcnt lgkmcnt(1)
	v_mfma_f32_32x32x16_bf16 v[80:95], v[180:183], v[128:131], v[80:95]
	s_waitcnt lgkmcnt(0)
	v_mfma_f32_32x32x16_bf16 v[64:79], v[222:225], v[128:131], v[64:79]
	ds_read_b128 v[180:183], v169 offset:49280
	ds_read_b128 v[222:225], v169 offset:62080
	s_waitcnt lgkmcnt(1)
	v_mfma_f32_32x32x16_bf16 v[80:95], v[180:183], v[124:127], v[80:95]
	s_waitcnt lgkmcnt(0)
	v_mfma_f32_32x32x16_bf16 v[64:79], v[222:225], v[124:127], v[64:79]
	ds_read_b128 v[180:183], v169 offset:49312
	ds_read_b128 v[222:225], v169 offset:62112
	s_waitcnt lgkmcnt(1)
	v_mfma_f32_32x32x16_bf16 v[80:95], v[180:183], v[120:123], v[80:95]
	s_waitcnt lgkmcnt(0)
	v_mfma_f32_32x32x16_bf16 v[64:79], v[222:225], v[120:123], v[64:79]
	ds_read_b128 v[180:183], v169 offset:49344
	ds_read_b128 v[222:225], v169 offset:62144
	s_waitcnt lgkmcnt(1)
	v_mfma_f32_32x32x16_bf16 v[80:95], v[180:183], v[116:119], v[80:95]
	s_waitcnt lgkmcnt(0)
	v_mfma_f32_32x32x16_bf16 v[64:79], v[222:225], v[116:119], v[64:79]
	ds_read_b128 v[180:183], v169 offset:49376
	ds_read_b128 v[222:225], v169 offset:62176
	s_waitcnt lgkmcnt(1)
	v_mfma_f32_32x32x16_bf16 v[80:95], v[180:183], v[112:115], v[80:95]
	s_waitcnt lgkmcnt(0)
	v_mfma_f32_32x32x16_bf16 v[64:79], v[222:225], v[112:115], v[64:79]
	ds_read_b128 v[180:183], v169 offset:49408
	ds_read_b128 v[222:225], v169 offset:62208
	s_waitcnt lgkmcnt(1)
	v_mfma_f32_32x32x16_bf16 v[80:95], v[180:183], v[108:111], v[80:95]
	s_waitcnt lgkmcnt(0)
	v_mfma_f32_32x32x16_bf16 v[64:79], v[222:225], v[108:111], v[64:79]
	ds_read_b128 v[180:183], v169 offset:49440
	ds_read_b128 v[222:225], v169 offset:62240
	s_waitcnt lgkmcnt(1)
	v_mfma_f32_32x32x16_bf16 v[80:95], v[180:183], v[104:107], v[80:95]
	s_waitcnt lgkmcnt(0)
	v_mfma_f32_32x32x16_bf16 v[64:79], v[222:225], v[104:107], v[64:79]
	ds_read_b128 v[180:183], v169 offset:49472
	ds_read_b128 v[222:225], v169 offset:62272
	s_waitcnt lgkmcnt(1)
	v_mfma_f32_32x32x16_bf16 v[80:95], v[180:183], v[100:103], v[80:95]
	s_waitcnt lgkmcnt(0)
	v_mfma_f32_32x32x16_bf16 v[64:79], v[222:225], v[100:103], v[64:79]
	ds_read_b128 v[180:183], v169 offset:49504
	ds_read_b128 v[222:225], v169 offset:62304
	v_exp_f32_e32 v169, v160
	v_cvt_pk_bf16_f32 v160, v198, v200
	v_add_f32_e32 v146, v169, v146
	s_waitcnt lgkmcnt(1)
	v_mfma_f32_32x32x16_bf16 v[80:95], v[180:183], v[96:99], v[80:95]
	v_exp_f32_e32 v180, v161
	v_exp_f32_e32 v183, v158
	v_cvt_pk_bf16_f32 v158, v184, v185
	v_cvt_pk_bf16_f32 v161, v214, v217
	v_add_f32_e32 v146, v180, v146
	v_cvt_pk_bf16_f32 v150, v169, v180
	v_add_f32_e32 v146, v183, v146
	s_nop 4
	v_max_f32_e32 v169, v81, v81
	v_max_f32_e32 v180, v80, v80
	s_waitcnt lgkmcnt(0)
; #define SBAR() __builtin_amdgcn_sched_barrier(0)
; template <int D0> __device__ __forceinline__ void pv_one_sm(f32x16& od, int vb, bf16x8 pa0, bf16x8 pa1, bf16x8 pa2, bf16x8 pa3, f32x16& q0, f32x16& q1, const float C, const float mnC) {
;   const s16x4 l0 = tr_read<v_rd_off(D0, 0, 0)>(vb), h0 = tr_read<v_rd_off(D0, 0, 1)>(vb), l1 = tr_read<v_rd_off(D0, 1, 0)>(vb), h1 = tr_read<v_rd_off(D0, 1, 1)>(vb);
;   const s16x4 l2 = tr_read<v_rd_off(D0, 2, 0)>(vb), h2 = tr_read<v_rd_off(D0, 2, 1)>(vb), l3 = tr_read<v_rd_off(D0, 3, 0)>(vb), h3 = tr_read<v_rd_off(D0, 3, 1)>(vb);
;   asm volatile("s_waitcnt lgkmcnt(0)" ::: "memory"); SBAR();
;     ...
;   od = __builtin_amdgcn_mfma_f32_32x32x16_bf16(pa0, PK(l0, h0), od, 0, 0, 0);
;   od = __builtin_amdgcn_mfma_f32_32x32x16_bf16(pa1, PK(l1, h1), od, 0, 0, 0);
;   od = __builtin_amdgcn_mfma_f32_32x32x16_bf16(pa2, PK(l2, h2), od, 0, 0, 0);
;   od = __builtin_amdgcn_mfma_f32_32x32x16_bf16(pa3, PK(l3, h3), od, 0, 0, 0);
;     ...
;   if (D0 < 2) {
; #pragma unroll
;     for (int r = 8 * D0; r < 8 * D0 + 8; ++r) q0[r] = __builtin_amdgcn_exp2f(fmaf(q0[r], C, mnC));
;   } else {
; #pragma unroll
;     for (int r = 8 * (D0 - 2); r < 8 * (D0 - 2) + 8; ++r) q1[r] = fmaf(q1[r], C, mnC);
;   }
; }
; __device__ __forceinline__ void pv_sm(f32x16* o, int vb, bf16x8 pa0, bf16x8 pa1, bf16x8 pa2, bf16x8 pa3, f32x16& q0, f32x16& q1, const float C, const float mn) {
;   const float mnC = -mn * C;
;   pv_one_sm<0>(o[0], vb, pa0, pa1, pa2, pa3, q0, q1, C, mnC); pv_one_sm<1>(o[1], vb, pa0, pa1, pa2, pa3, q0, q1, C, mnC);
;   pv_one_sm<2>(o[2], vb, pa0, pa1, pa2, pa3, q0, q1, C, mnC); pv_one_sm<3>(o[3], vb, pa0, pa1, pa2, pa3, q0, q1, C, mnC);
; }
	v_mfma_f32_32x32x16_bf16 v[64:79], v[222:225], v[96:99], v[64:79]
	v_max_f32_e32 v169, v180, v169
	v_max3_f32 v169, v169, v82, v83
	v_max3_f32 v169, v169, v84, v85
	v_max3_f32 v169, v169, v86, v87
	v_max3_f32 v169, v169, v88, v89
	v_max3_f32 v169, v169, v90, v91
	v_exp_f32_e32 v222, v159
	v_max3_f32 v169, v169, v92, v93
	v_exp_f32_e32 v223, v156
	v_max3_f32 v169, v169, v94, v95
	v_exp_f32_e32 v224, v157
	s_nop 0
	v_max3_f32 v169, v169, v64, v65
	v_exp_f32_e32 v225, v154
	v_max3_f32 v169, v169, v66, v67
	v_add_f32_e32 v146, v222, v146
	v_max3_f32 v169, v169, v68, v69
	v_add_f32_e32 v146, v223, v146
	v_max3_f32 v169, v169, v70, v71
	v_add_f32_e32 v146, v224, v146
	v_max3_f32 v169, v169, v72, v73
	v_add_f32_e32 v146, v225, v146
	v_max3_f32 v169, v169, v74, v75
	v_add_f32_e32 v146, v226, v146
	v_max3_f32 v169, v169, v76, v77
	v_add_f32_e32 v146, v227, v146
	v_max3_f32 v169, v169, v78, v79
	v_add_f32_e32 v146, v228, v146
	v_mov_b32_e32 v180, v169
	v_add_f32_e32 v146, v229, v146
	s_nop 0
	v_permlane32_swap_b32_e32 v169, v180
	v_add_f32_e32 v146, v230, v146
	v_max_f32_e32 v180, v180, v180
	v_max_f32_e32 v169, v169, v169
	v_add_f32_e32 v146, v148, v146
	v_max_f32_e32 v169, v169, v180
	v_add_f32_e32 v146, v149, v146
	v_sub_f32_e32 v180, v169, v178
	v_add_f32_e32 v146, v231, v146
	v_cmp_ge_f32_e32 vcc, s56, v180
	v_max_f32_e32 v180, v178, v178
	v_add_f32_e32 v181, v232, v146
	v_max_f32_e32 v180, v180, v169
	v_mov_b32_e32 v182, v181
	s_cmp_eq_u64 vcc, exec
	v_sub_f32_e32 v169, v178, v180
	v_permlane32_swap_b32_e32 v181, v182
	s_cselect_b64 s[8:9], -1, 0
	v_mul_f32_e32 v169, 0x3dd53b94, v169
	v_cvt_pk_bf16_f32 v159, v189, v191
	v_cvt_pk_bf16_f32 v154, v215, v218
	v_cvt_pk_bf16_f32 v156, v216, v219
	v_cvt_pk_bf16_f32 v157, v220, v221
	v_cvt_pk_bf16_f32 v151, v183, v222
	v_cvt_pk_bf16_f32 v152, v223, v224
	v_cvt_pk_bf16_f32 v153, v225, v226
	v_cvt_pk_bf16_f32 v146, v227, v228
	v_cvt_pk_bf16_f32 v148, v148, v149
	v_cvt_pk_bf16_f32 v149, v231, v232
	s_add_i32 s10, s13, 0xfffe8000
	s_mov_b32 s38, s30
	s_mov_b32 s39, s31
	s_add_i32 s11, s13, 0xffff0000
	buffer_load_dwordx4 v[198:201], v170, s[28:31], s10 offen
	buffer_load_dwordx4 v[214:217], v170, s[28:31], s11 offen
	buffer_load_dwordx4 v[218:221], v171, s[36:39], s12 offen
	buffer_load_dwordx4 v[222:225], v176, s[36:39], s12 offen
	buffer_load_dwordx4 v[226:229], v177, s[36:39], s12 offen
	v_exp_f32_e32 v183, v169
	s_lshl_b32 s16, s44, 14
	v_add_u32_e32 v169, s16, v168
	ds_read_b64_tr_b16 v[230:231], v169 offset:0
	ds_read_b64_tr_b16 v[232:233], v169 offset:0x800
	ds_read_b64_tr_b16 v[234:235], v169 offset:0x1000
	ds_read_b64_tr_b16 v[236:237], v169 offset:0x1800
	ds_read_b64_tr_b16 v[238:239], v169 offset:0x2000
	ds_read_b64_tr_b16 v[240:241], v169 offset:0x2800
	ds_read_b64_tr_b16 v[242:243], v169 offset:0x3000
	ds_read_b64_tr_b16 v[244:245], v169 offset:0x3800
	s_waitcnt lgkmcnt(0)
	s_nop 0
	v_mfma_f32_32x32x16_bf16 v[0:15], v[158:161], v[230:233], v[0:15]
	ds_read_b64_tr_b16 v[230:231], v169 offset:0x200
	ds_read_b64_tr_b16 v[232:233], v169 offset:0xa00
	v_mfma_f32_32x32x16_bf16 v[0:15], v[154:157], v[234:237], v[0:15]
	ds_read_b64_tr_b16 v[234:235], v169 offset:0x1200
	ds_read_b64_tr_b16 v[236:237], v169 offset:0x1a00
	v_mfma_f32_32x32x16_bf16 v[0:15], v[150:153], v[238:241], v[0:15]
	ds_read_b64_tr_b16 v[238:239], v169 offset:0x2200
	ds_read_b64_tr_b16 v[240:241], v169 offset:0x2a00
	v_mfma_f32_32x32x16_bf16 v[0:15], v[146:149], v[242:245], v[0:15]
	ds_read_b64_tr_b16 v[242:243], v169 offset:0x3200
	ds_read_b64_tr_b16 v[244:245], v169 offset:0x3a00
	s_waitcnt lgkmcnt(0)
	v_mfma_f32_32x32x16_bf16 v[48:63], v[158:161], v[230:233], v[48:63]
	ds_read_b64_tr_b16 v[230:231], v169 offset:0x400
	ds_read_b64_tr_b16 v[232:233], v169 offset:0xc00
	v_mfma_f32_32x32x16_bf16 v[48:63], v[154:157], v[234:237], v[48:63]
	ds_read_b64_tr_b16 v[234:235], v169 offset:0x1400
	ds_read_b64_tr_b16 v[236:237], v169 offset:0x1c00
	v_mfma_f32_32x32x16_bf16 v[48:63], v[150:153], v[238:241], v[48:63]
	ds_read_b64_tr_b16 v[238:239], v169 offset:0x2400
	ds_read_b64_tr_b16 v[240:241], v169 offset:0x2c00
	v_mfma_f32_32x32x16_bf16 v[48:63], v[146:149], v[242:245], v[48:63]
	ds_read_b64_tr_b16 v[242:243], v169 offset:0x3400
	ds_read_b64_tr_b16 v[244:245], v169 offset:0x3c00
	s_waitcnt lgkmcnt(0)
	v_mfma_f32_32x32x16_bf16 v[32:47], v[158:161], v[230:233], v[32:47]
	ds_read_b64_tr_b16 v[230:231], v169 offset:0x600
	ds_read_b64_tr_b16 v[232:233], v169 offset:0xe00
	v_mfma_f32_32x32x16_bf16 v[32:47], v[154:157], v[234:237], v[32:47]
	ds_read_b64_tr_b16 v[234:235], v169 offset:0x1600
	ds_read_b64_tr_b16 v[236:237], v169 offset:0x1e00
	v_mfma_f32_32x32x16_bf16 v[32:47], v[150:153], v[238:241], v[32:47]
	ds_read_b64_tr_b16 v[238:239], v169 offset:0x2600
	ds_read_b64_tr_b16 v[240:241], v169 offset:0x2e00
	v_mfma_f32_32x32x16_bf16 v[32:47], v[146:149], v[242:245], v[32:47]
	ds_read_b64_tr_b16 v[242:243], v169 offset:0x3600
	ds_read_b64_tr_b16 v[244:245], v169 offset:0x3e00
	s_waitcnt lgkmcnt(0)
	v_mfma_f32_32x32x16_bf16 v[16:31], v[158:161], v[230:233], v[16:31]
	s_lshl_b32 s15, s51, 14
	s_mul_i32 s17, s51, 0x6400
	v_cndmask_b32_e64 v183, v183, 1.0, s[8:9]
	v_cmp_gt_f32_e32 vcc, 1.0, v183
	v_mfma_f32_32x32x16_bf16 v[16:31], v[154:157], v[234:237], v[16:31]
	v_add_u32_e32 v154, s15, v175
	s_waitcnt vmcnt(4)
	ds_write_b128 v154, v[198:201]
	s_waitcnt vmcnt(3)
	ds_write_b128 v154, v[214:217] offset:8192
	v_mfma_f32_32x32x16_bf16 v[16:31], v[150:153], v[238:241], v[16:31]
	v_add_u32_e32 v150, s17, v173
	s_waitcnt vmcnt(2)
	ds_write_b128 v150, v[218:221] offset:49152
	s_waitcnt vmcnt(1)
	ds_write_b128 v150, v[222:225] offset:49280
	s_waitcnt vmcnt(0)
	ds_write_b128 v150, v[226:229] offset:49408
	v_mfma_f32_32x32x16_bf16 v[16:31], v[146:149], v[242:245], v[16:31]
	s_cbranch_vccz .LBB0_2543
; #define SBAR() __builtin_amdgcn_sched_barrier(0)
; #define QKT(P0, P1, KS) do { if constexpr (MI) qkt_mi<NQK>(P0, P1, KS, qr, r32, hi, minit); else qkt<NQK>(P0, P1, KS, qr, r32, hi); } while (0)
; #define DECIDE(P0, P1, MN, AL) do { if constexpr (MI) decide_mi(P0, P1, minit, Mref, AL, thr2, false); else decideSM(P0, P1, m_reg, MN, AL, C, thr); } while (0)
; template <int NQK, int SD, bool MI> ...
;     ...
;     SBAR(); QKT(pA0, pA1, K_lds + rc * KT);
;     finishSM(pB0, pB1, alB, l_reg, pa0, pa1, pa2, pa3); DECIDE(pA0, pA1, mnA, alA); SBAR();
	s_and_saveexec_b64 s[10:11], s[6:7]
	ds_write_b32 v166, v183 offset:128
	s_or_b64 exec, exec, s[10:11]
	s_waitcnt lgkmcnt(0)
	v_add_u32_e32 v158, v165, v162
	ds_read_b128 v[146:149], v158 offset:224
	ds_read_b128 v[150:153], v158 offset:192
	ds_read_b128 v[154:157], v158 offset:160
	ds_read_b128 v[158:161], v158 offset:128
	s_waitcnt lgkmcnt(3)
	v_pk_mul_f32 v[12:13], v[12:13], v[146:147]
	s_waitcnt lgkmcnt(2)
	v_pk_mul_f32 v[8:9], v[8:9], v[150:151]
	s_waitcnt lgkmcnt(1)
	v_pk_mul_f32 v[4:5], v[4:5], v[154:155]
	v_pk_mul_f32 v[14:15], v[14:15], v[148:149]
	v_pk_mul_f32 v[10:11], v[10:11], v[152:153]
	v_pk_mul_f32 v[6:7], v[6:7], v[156:157]
	s_waitcnt lgkmcnt(0)
	v_pk_mul_f32 v[2:3], v[2:3], v[160:161]
	v_pk_mul_f32 v[0:1], v[0:1], v[158:159]
	v_pk_mul_f32 v[60:61], v[60:61], v[146:147]
	v_pk_mul_f32 v[56:57], v[56:57], v[150:151]
	v_pk_mul_f32 v[52:53], v[52:53], v[154:155]
	v_pk_mul_f32 v[62:63], v[62:63], v[148:149]
	v_pk_mul_f32 v[58:59], v[58:59], v[152:153]
	v_pk_mul_f32 v[54:55], v[54:55], v[156:157]
	v_pk_mul_f32 v[50:51], v[50:51], v[160:161]
	v_pk_mul_f32 v[48:49], v[48:49], v[158:159]
	v_pk_mul_f32 v[44:45], v[44:45], v[146:147]
	v_pk_mul_f32 v[40:41], v[40:41], v[150:151]
	v_pk_mul_f32 v[36:37], v[36:37], v[154:155]
	v_pk_mul_f32 v[46:47], v[46:47], v[148:149]
	v_pk_mul_f32 v[42:43], v[42:43], v[152:153]
	v_pk_mul_f32 v[38:39], v[38:39], v[156:157]
	v_pk_mul_f32 v[34:35], v[34:35], v[160:161]
	v_pk_mul_f32 v[32:33], v[32:33], v[158:159]
	v_pk_mul_f32 v[28:29], v[28:29], v[146:147]
	v_pk_mul_f32 v[24:25], v[24:25], v[150:151]
	v_pk_mul_f32 v[20:21], v[20:21], v[154:155]
	v_pk_mul_f32 v[30:31], v[30:31], v[148:149]
	v_pk_mul_f32 v[26:27], v[26:27], v[152:153]
	v_pk_mul_f32 v[22:23], v[22:23], v[156:157]
	v_pk_mul_f32 v[18:19], v[18:19], v[160:161]
	v_pk_mul_f32 v[16:17], v[16:17], v[158:159]
.LBB0_2543:
	v_cndmask_b32_e64 v178, v180, v178, s[8:9]
	v_mul_f32_e32 v154, 0xbdd53b94, v178
	v_fmamk_f32 v80, v80, 0x3dd53b94, v154
	v_exp_f32_e32 v155, v80
	v_fmamk_f32 v80, v81, 0x3dd53b94, v154
	v_exp_f32_e32 v156, v80
	v_fmamk_f32 v80, v82, 0x3dd53b94, v154
	v_exp_f32_e32 v157, v80
	v_fmamk_f32 v80, v83, 0x3dd53b94, v154
	v_exp_f32_e32 v159, v80
	v_fmamk_f32 v80, v84, 0x3dd53b94, v154
	v_exp_f32_e32 v160, v80
	v_fmamk_f32 v80, v85, 0x3dd53b94, v154
	v_exp_f32_e32 v161, v80
	v_fmamk_f32 v80, v86, 0x3dd53b94, v154
	v_exp_f32_e32 v180, v80
	v_fmamk_f32 v80, v87, 0x3dd53b94, v154
	v_exp_f32_e32 v189, v80
	v_fmamk_f32 v80, v88, 0x3dd53b94, v154
	v_exp_f32_e32 v191, v80
	v_fmamk_f32 v80, v89, 0x3dd53b94, v154
	v_exp_f32_e32 v198, v80
	v_fmamk_f32 v80, v90, 0x3dd53b94, v154
	v_exp_f32_e32 v199, v80
	v_fmamk_f32 v80, v91, 0x3dd53b94, v154
	v_exp_f32_e32 v200, v80
	v_fmamk_f32 v80, v92, 0x3dd53b94, v154
	v_exp_f32_e32 v201, v80
	v_fmamk_f32 v80, v93, 0x3dd53b94, v154
	v_exp_f32_e32 v214, v80
	v_fmamk_f32 v80, v94, 0x3dd53b94, v154
	v_exp_f32_e32 v215, v80
	v_fmamk_f32 v80, v95, 0x3dd53b94, v154
	v_fmamk_f32 v184, v66, 0x3dd53b94, v154
	v_fmamk_f32 v185, v68, 0x3dd53b94, v154
	v_exp_f32_e32 v216, v80
	v_fmamk_f32 v158, v64, 0x3dd53b94, v154
	v_fmamk_f32 v217, v70, 0x3dd53b94, v154
	v_fmamk_f32 v218, v65, 0x3dd53b94, v154
	v_fmamk_f32 v219, v67, 0x3dd53b94, v154
	v_fmamk_f32 v220, v69, 0x3dd53b94, v154
	v_fmamk_f32 v221, v71, 0x3dd53b94, v154
	v_fmamk_f32 v222, v72, 0x3dd53b94, v154
	v_fmamk_f32 v223, v73, 0x3dd53b94, v154
	v_fmamk_f32 v224, v74, 0x3dd53b94, v154
	v_fmamk_f32 v225, v75, 0x3dd53b94, v154
	v_fmamk_f32 v226, v76, 0x3dd53b94, v154
	v_fmamk_f32 v227, v77, 0x3dd53b94, v154
	v_fmamk_f32 v228, v78, 0x3dd53b94, v154
	v_fmac_f32_e32 v154, 0x3dd53b94, v79
	s_waitcnt lgkmcnt(0)
	s_barrier
	v_add_u32_e32 v229, s17, v174
	ds_read_b128 v[64:67], v229 offset:61952
	ds_read_b128 v[68:71], v229 offset:49152
	ds_read_b128 v[146:149], v229 offset:49184
	ds_read_b128 v[150:153], v229 offset:61984
	v_exp_f32_e32 v217, v217
	s_waitcnt lgkmcnt(2)
	v_mfma_f32_32x32x16_bf16 v[80:95], v[68:71], v[140:143], 0
	v_mfma_f32_32x32x16_bf16 v[64:79], v[64:67], v[140:143], 0
	s_waitcnt lgkmcnt(1)
	v_mfma_f32_32x32x16_bf16 v[80:95], v[146:149], v[136:139], v[80:95]
	s_waitcnt lgkmcnt(0)
	v_mfma_f32_32x32x16_bf16 v[64:79], v[150:153], v[136:139], v[64:79]
	ds_read_b128 v[146:149], v229 offset:49216
	ds_read_b128 v[150:153], v229 offset:62016
	s_waitcnt lgkmcnt(1)
	v_mfma_f32_32x32x16_bf16 v[80:95], v[146:149], v[132:135], v[80:95]
	s_waitcnt lgkmcnt(0)
	v_mfma_f32_32x32x16_bf16 v[64:79], v[150:153], v[132:135], v[64:79]
	ds_read_b128 v[146:149], v229 offset:49248
	ds_read_b128 v[150:153], v229 offset:62048
	s_waitcnt lgkmcnt(1)
	v_mfma_f32_32x32x16_bf16 v[80:95], v[146:149], v[128:131], v[80:95]
	s_waitcnt lgkmcnt(0)
	v_mfma_f32_32x32x16_bf16 v[64:79], v[150:153], v[128:131], v[64:79]
	ds_read_b128 v[146:149], v229 offset:49280
	ds_read_b128 v[150:153], v229 offset:62080
	s_waitcnt lgkmcnt(1)
	v_mfma_f32_32x32x16_bf16 v[80:95], v[146:149], v[124:127], v[80:95]
	s_waitcnt lgkmcnt(0)
	v_mfma_f32_32x32x16_bf16 v[64:79], v[150:153], v[124:127], v[64:79]
	ds_read_b128 v[146:149], v229 offset:49312
	ds_read_b128 v[150:153], v229 offset:62112
	s_waitcnt lgkmcnt(1)
	v_mfma_f32_32x32x16_bf16 v[80:95], v[146:149], v[120:123], v[80:95]
	s_waitcnt lgkmcnt(0)
	v_mfma_f32_32x32x16_bf16 v[64:79], v[150:153], v[120:123], v[64:79]
	ds_read_b128 v[146:149], v229 offset:49344
	ds_read_b128 v[150:153], v229 offset:62144
	s_waitcnt lgkmcnt(1)
	v_mfma_f32_32x32x16_bf16 v[80:95], v[146:149], v[116:119], v[80:95]
	s_waitcnt lgkmcnt(0)
	v_mfma_f32_32x32x16_bf16 v[64:79], v[150:153], v[116:119], v[64:79]
	ds_read_b128 v[146:149], v229 offset:49376
	ds_read_b128 v[150:153], v229 offset:62176
	s_waitcnt lgkmcnt(1)
; #define SBAR() __builtin_amdgcn_sched_barrier(0)
; #define SWRITE(b, i) do { STG_T() const int _sv = VSTV(), _sk = LDSK(); *(u32x4*)(V_lds + (b) * SHM_V + _sv) = sr_[i].vs0; *(u32x4*)(V_lds + (b) * SHM_V + _sv + 8192) = sr_[i].vs1; \
;     _Pragma("unroll") for (int _p = 0; _p < NP; ++_p) *(u32x4*)(K_lds + (b) * KT + _sk + _p * 128) = sr_[i].ks[_p]; } while (0)
; #define SWAIT() do { if constexpr (SD == 2) { if constexpr (NP == 1) asm volatile("s_waitcnt vmcnt(3)" ::: "memory"); else asm volatile("s_waitcnt vmcnt(5)" ::: "memory"); } else asm volatile("s_waitcnt vmcnt(0)" ::: "memory"); } while (0)
; #define QKT(P0, P1, KS) do { if constexpr (MI) qkt_mi<NQK>(P0, P1, KS, qr, r32, hi, minit); else qkt<NQK>(P0, P1, KS, qr, r32, hi); } while (0)
; #define DECIDE(P0, P1, MN, AL) do { if constexpr (MI) decide_mi(P0, P1, minit, Mref, AL, thr2, false); else decideSM(P0, P1, m_reg, MN, AL, C, thr); } while (0)
; #define PVSM(VB, P0, P1, MN) do { if constexpr (MI) pv_mi(o, VB, pa0, pa1, pa2, pa3, P0); else pv_sm(o, VB, pa0, pa1, pa2, pa3, P0, P1, C, MN); } while (0)
; template <int NQK, int SD, bool MI> ...
;     ...
;     SBAR(); QKT(pA0, pA1, K_lds + rc * KT);
;     finishSM(pB0, pB1, alB, l_reg, pa0, pa1, pa2, pa3); DECIDE(pA0, pA1, mnA, alA); SBAR();
;     if (SD == 1 || j + 3 < NT) SLOAD(SE, (j + 1 + SD) * 64); SBAR();
;     PVSM(vb0 + rp * SHM_V, pA0, pA1, mnA);
;     SWAIT(); SWRITE(rn, SO);
	v_mfma_f32_32x32x16_bf16 v[80:95], v[146:149], v[112:115], v[80:95]
	s_waitcnt lgkmcnt(0)
	v_mfma_f32_32x32x16_bf16 v[64:79], v[150:153], v[112:115], v[64:79]
	ds_read_b128 v[146:149], v229 offset:49408
	ds_read_b128 v[150:153], v229 offset:62208
	s_waitcnt lgkmcnt(1)
	v_mfma_f32_32x32x16_bf16 v[80:95], v[146:149], v[108:111], v[80:95]
	s_waitcnt lgkmcnt(0)
	v_mfma_f32_32x32x16_bf16 v[64:79], v[150:153], v[108:111], v[64:79]
	ds_read_b128 v[146:149], v229 offset:49440
	ds_read_b128 v[150:153], v229 offset:62240
	s_waitcnt lgkmcnt(1)
	v_mfma_f32_32x32x16_bf16 v[80:95], v[146:149], v[104:107], v[80:95]
	s_waitcnt lgkmcnt(0)
	v_mfma_f32_32x32x16_bf16 v[64:79], v[150:153], v[104:107], v[64:79]
	ds_read_b128 v[146:149], v229 offset:49472
	ds_read_b128 v[150:153], v229 offset:62272
	s_waitcnt lgkmcnt(1)
	v_mfma_f32_32x32x16_bf16 v[80:95], v[146:149], v[100:103], v[80:95]
	s_waitcnt lgkmcnt(0)
	v_mfma_f32_32x32x16_bf16 v[64:79], v[150:153], v[100:103], v[64:79]
	ds_read_b128 v[146:149], v229 offset:49504
	ds_read_b128 v[150:153], v229 offset:62304
	s_waitcnt lgkmcnt(1)
	v_mfma_f32_32x32x16_bf16 v[80:95], v[146:149], v[96:99], v[80:95]
	v_exp_f32_e32 v146, v158
	v_exp_f32_e32 v147, v218
	v_exp_f32_e32 v148, v184
	v_exp_f32_e32 v149, v219
	v_exp_f32_e32 v218, v221
	v_exp_f32_e32 v219, v222
	v_exp_f32_e32 v221, v224
	s_waitcnt lgkmcnt(0)
	v_mfma_f32_32x32x16_bf16 v[64:79], v[150:153], v[96:99], v[64:79]
	v_add_f32_e32 v150, 0, v155
	v_add_f32_e32 v150, v156, v150
	v_add_f32_e32 v150, v157, v150
	v_add_f32_e32 v150, v159, v150
	v_add_f32_e32 v150, v160, v150
	v_add_f32_e32 v150, v161, v150
	v_add_f32_e32 v150, v180, v150
	v_add_f32_e32 v150, v189, v150
	v_add_f32_e32 v150, v191, v150
	v_cvt_pk_bf16_f32 v160, v160, v161
	v_cvt_pk_bf16_f32 v161, v180, v189
	v_max_f32_e32 v180, v81, v81
	v_max_f32_e32 v189, v80, v80
	v_add_f32_e32 v150, v198, v150
	v_max_f32_e32 v180, v189, v180
	v_add_f32_e32 v150, v199, v150
	v_max3_f32 v180, v180, v82, v83
	v_add_f32_e32 v150, v200, v150
	v_max3_f32 v180, v180, v84, v85
	v_add_f32_e32 v150, v201, v150
	v_max3_f32 v180, v180, v86, v87
	v_add_f32_e32 v150, v214, v150
	v_max3_f32 v180, v180, v88, v89
	v_add_f32_e32 v150, v215, v150
	v_max3_f32 v180, v180, v90, v91
	v_add_f32_e32 v150, v216, v150
	v_max3_f32 v180, v180, v92, v93
	v_exp_f32_e32 v152, v185
	v_add_f32_e32 v150, v146, v150
	v_max3_f32 v180, v180, v94, v95
	v_exp_f32_e32 v153, v220
	v_add_f32_e32 v150, v147, v150
	v_max3_f32 v180, v180, v64, v65
	v_add_f32_e32 v150, v148, v150
	v_max3_f32 v180, v180, v66, v67
	v_add_f32_e32 v150, v149, v150
	v_max3_f32 v180, v180, v68, v69
	v_add_f32_e32 v150, v152, v150
	v_max3_f32 v180, v180, v70, v71
	v_exp_f32_e32 v220, v223
	v_add_f32_e32 v150, v153, v150
	v_max3_f32 v180, v180, v72, v73
	v_add_f32_e32 v150, v217, v150
	v_max3_f32 v180, v180, v74, v75
	v_exp_f32_e32 v222, v225
	v_add_f32_e32 v150, v218, v150
	v_max3_f32 v180, v180, v76, v77
	v_exp_f32_e32 v223, v226
	v_add_f32_e32 v150, v219, v150
	v_max3_f32 v180, v180, v78, v79
	v_exp_f32_e32 v224, v227
	v_add_f32_e32 v150, v220, v150
	v_mov_b32_e32 v189, v180
	v_exp_f32_e32 v225, v228
	v_add_f32_e32 v150, v221, v150
	v_permlane32_swap_b32_e32 v180, v189
	v_exp_f32_e32 v226, v154
	v_add_f32_e32 v150, v222, v150
	v_max_f32_e32 v189, v189, v189
	v_max_f32_e32 v180, v180, v180
	v_add_f32_e32 v150, v223, v150
	v_max_f32_e32 v180, v180, v189
	v_add_f32_e32 v150, v224, v150
	v_sub_f32_e32 v189, v180, v178
	v_add_f32_e32 v150, v225, v150
	v_cmp_ge_f32_e32 vcc, s56, v189
	v_max_f32_e32 v189, v178, v178
	v_add_f32_e32 v184, v226, v150
	v_max_f32_e32 v189, v189, v180
	v_mov_b32_e32 v185, v184
	s_cmp_eq_u64 vcc, exec
	v_sub_f32_e32 v180, v178, v189
	v_permlane32_swap_b32_e32 v184, v185
	s_cselect_b64 s[8:9], -1, 0
	v_mul_f32_e32 v180, 0x3dd53b94, v180
	v_cvt_pk_bf16_f32 v158, v155, v156
	v_cvt_pk_bf16_f32 v159, v157, v159
	v_cvt_pk_bf16_f32 v154, v191, v198
	v_cvt_pk_bf16_f32 v155, v199, v200
	v_cvt_pk_bf16_f32 v156, v201, v214
	v_cvt_pk_bf16_f32 v157, v215, v216
	v_cvt_pk_bf16_f32 v150, v146, v147
	v_cvt_pk_bf16_f32 v151, v148, v149
	v_cvt_pk_bf16_f32 v152, v152, v153
	v_cvt_pk_bf16_f32 v153, v217, v218
	v_cvt_pk_bf16_f32 v146, v219, v220
	v_cvt_pk_bf16_f32 v147, v221, v222
	v_cvt_pk_bf16_f32 v148, v223, v224
	v_cvt_pk_bf16_f32 v149, v225, v226
	s_add_i32 s10, s13, 0xffff8000
	s_add_i32 s11, s12, 0x18000
	s_mov_b32 s38, s30
	s_mov_b32 s39, s31
	buffer_load_dwordx4 v[198:201], v170, s[28:31], s10 offen
	buffer_load_dwordx4 v[214:217], v170, s[28:31], s13 offen
	buffer_load_dwordx4 v[218:221], v171, s[36:39], s11 offen
	buffer_load_dwordx4 v[222:225], v176, s[36:39], s11 offen
	buffer_load_dwordx4 v[226:229], v177, s[36:39], s11 offen
	v_exp_f32_e32 v180, v180
	v_lshl_add_u32 v191, s14, 14, v168
	ds_read_b64_tr_b16 v[230:231], v191 offset:0
	ds_read_b64_tr_b16 v[232:233], v191 offset:0x800
	ds_read_b64_tr_b16 v[234:235], v191 offset:0x1000
	ds_read_b64_tr_b16 v[236:237], v191 offset:0x1800
	ds_read_b64_tr_b16 v[238:239], v191 offset:0x2000
	ds_read_b64_tr_b16 v[240:241], v191 offset:0x2800
	ds_read_b64_tr_b16 v[242:243], v191 offset:0x3000
	ds_read_b64_tr_b16 v[244:245], v191 offset:0x3800
	s_waitcnt lgkmcnt(0)
; #define SBAR() __builtin_amdgcn_sched_barrier(0)
; #define SWRITE(b, i) do { STG_T() const int _sv = VSTV(), _sk = LDSK(); *(u32x4*)(V_lds + (b) * SHM_V + _sv) = sr_[i].vs0; *(u32x4*)(V_lds + (b) * SHM_V + _sv + 8192) = sr_[i].vs1; \
;     _Pragma("unroll") for (int _p = 0; _p < NP; ++_p) *(u32x4*)(K_lds + (b) * KT + _sk + _p * 128) = sr_[i].ks[_p]; } while (0)
; #define SWAIT() do { if constexpr (SD == 2) { if constexpr (NP == 1) asm volatile("s_waitcnt vmcnt(3)" ::: "memory"); else asm volatile("s_waitcnt vmcnt(5)" ::: "memory"); } else asm volatile("s_waitcnt vmcnt(0)" ::: "memory"); } while (0)
; template <int D0> __device__ __forceinline__ void pv_one_sm(f32x16& od, int vb, bf16x8 pa0, bf16x8 pa1, bf16x8 pa2, bf16x8 pa3, f32x16& q0, f32x16& q1, const float C, const float mnC) {
;   const s16x4 l0 = tr_read<v_rd_off(D0, 0, 0)>(vb), h0 = tr_read<v_rd_off(D0, 0, 1)>(vb), l1 = tr_read<v_rd_off(D0, 1, 0)>(vb), h1 = tr_read<v_rd_off(D0, 1, 1)>(vb);
;   const s16x4 l2 = tr_read<v_rd_off(D0, 2, 0)>(vb), h2 = tr_read<v_rd_off(D0, 2, 1)>(vb), l3 = tr_read<v_rd_off(D0, 3, 0)>(vb), h3 = tr_read<v_rd_off(D0, 3, 1)>(vb);
;   asm volatile("s_waitcnt lgkmcnt(0)" ::: "memory"); SBAR();
;     ...
;   od = __builtin_amdgcn_mfma_f32_32x32x16_bf16(pa0, PK(l0, h0), od, 0, 0, 0);
;   od = __builtin_amdgcn_mfma_f32_32x32x16_bf16(pa1, PK(l1, h1), od, 0, 0, 0);
;   od = __builtin_amdgcn_mfma_f32_32x32x16_bf16(pa2, PK(l2, h2), od, 0, 0, 0);
;   od = __builtin_amdgcn_mfma_f32_32x32x16_bf16(pa3, PK(l3, h3), od, 0, 0, 0);
;     ...
;   if (D0 < 2) {
; #pragma unroll
;     for (int r = 8 * D0; r < 8 * D0 + 8; ++r) q0[r] = __builtin_amdgcn_exp2f(fmaf(q0[r], C, mnC));
;   } else {
; #pragma unroll
;     for (int r = 8 * (D0 - 2); r < 8 * (D0 - 2) + 8; ++r) q1[r] = fmaf(q1[r], C, mnC);
;   }
; }
; __device__ __forceinline__ void pv_sm(f32x16* o, int vb, bf16x8 pa0, bf16x8 pa1, bf16x8 pa2, bf16x8 pa3, f32x16& q0, f32x16& q1, const float C, const float mn) {
;   const float mnC = -mn * C;
;   pv_one_sm<0>(o[0], vb, pa0, pa1, pa2, pa3, q0, q1, C, mnC); pv_one_sm<1>(o[1], vb, pa0, pa1, pa2, pa3, q0, q1, C, mnC);
;   pv_one_sm<2>(o[2], vb, pa0, pa1, pa2, pa3, q0, q1, C, mnC); pv_one_sm<3>(o[3], vb, pa0, pa1, pa2, pa3, q0, q1, C, mnC);
; }
; template <int NQK, int SD, bool MI> ...
;     ...
;     PVSM(vb0 + rp * SHM_V, pA0, pA1, mnA);
;     SWAIT(); SWRITE(rn, SO);
;     RESC(alA); __syncthreads(); ROT();
	s_nop 0
	v_mfma_f32_32x32x16_bf16 v[0:15], v[158:161], v[230:233], v[0:15]
	ds_read_b64_tr_b16 v[230:231], v191 offset:0x200
	ds_read_b64_tr_b16 v[232:233], v191 offset:0xa00
	v_mfma_f32_32x32x16_bf16 v[0:15], v[154:157], v[234:237], v[0:15]
	ds_read_b64_tr_b16 v[234:235], v191 offset:0x1200
	ds_read_b64_tr_b16 v[236:237], v191 offset:0x1a00
	v_mfma_f32_32x32x16_bf16 v[0:15], v[150:153], v[238:241], v[0:15]
	ds_read_b64_tr_b16 v[238:239], v191 offset:0x2200
	ds_read_b64_tr_b16 v[240:241], v191 offset:0x2a00
	v_mfma_f32_32x32x16_bf16 v[0:15], v[146:149], v[242:245], v[0:15]
	ds_read_b64_tr_b16 v[242:243], v191 offset:0x3200
	ds_read_b64_tr_b16 v[244:245], v191 offset:0x3a00
	s_waitcnt lgkmcnt(0)
	v_mfma_f32_32x32x16_bf16 v[48:63], v[158:161], v[230:233], v[48:63]
	ds_read_b64_tr_b16 v[230:231], v191 offset:0x400
	ds_read_b64_tr_b16 v[232:233], v191 offset:0xc00
	v_mfma_f32_32x32x16_bf16 v[48:63], v[154:157], v[234:237], v[48:63]
	ds_read_b64_tr_b16 v[234:235], v191 offset:0x1400
	ds_read_b64_tr_b16 v[236:237], v191 offset:0x1c00
	v_mfma_f32_32x32x16_bf16 v[48:63], v[150:153], v[238:241], v[48:63]
	ds_read_b64_tr_b16 v[238:239], v191 offset:0x2400
	ds_read_b64_tr_b16 v[240:241], v191 offset:0x2c00
	v_mfma_f32_32x32x16_bf16 v[48:63], v[146:149], v[242:245], v[48:63]
	ds_read_b64_tr_b16 v[242:243], v191 offset:0x3400
	ds_read_b64_tr_b16 v[244:245], v191 offset:0x3c00
	s_waitcnt lgkmcnt(0)
	v_mfma_f32_32x32x16_bf16 v[32:47], v[158:161], v[230:233], v[32:47]
	ds_read_b64_tr_b16 v[230:231], v191 offset:0x600
	ds_read_b64_tr_b16 v[232:233], v191 offset:0xe00
	v_mfma_f32_32x32x16_bf16 v[32:47], v[154:157], v[234:237], v[32:47]
	ds_read_b64_tr_b16 v[234:235], v191 offset:0x1600
	ds_read_b64_tr_b16 v[236:237], v191 offset:0x1e00
	v_mfma_f32_32x32x16_bf16 v[32:47], v[150:153], v[238:241], v[32:47]
	ds_read_b64_tr_b16 v[238:239], v191 offset:0x2600
	ds_read_b64_tr_b16 v[240:241], v191 offset:0x2e00
	v_mfma_f32_32x32x16_bf16 v[32:47], v[146:149], v[242:245], v[32:47]
	ds_read_b64_tr_b16 v[242:243], v191 offset:0x3600
	ds_read_b64_tr_b16 v[244:245], v191 offset:0x3e00
	s_waitcnt lgkmcnt(0)
	v_mfma_f32_32x32x16_bf16 v[16:31], v[158:161], v[230:233], v[16:31]
	v_cndmask_b32_e64 v180, v180, 1.0, s[8:9]
	v_cmp_gt_f32_e32 vcc, 1.0, v180
	v_mfma_f32_32x32x16_bf16 v[16:31], v[154:157], v[234:237], v[16:31]
	v_add_u32_e32 v154, s16, v175
	s_mul_i32 s16, s44, 0x6400
	s_waitcnt vmcnt(4)
	ds_write_b128 v154, v[198:201]
	s_waitcnt vmcnt(3)
	ds_write_b128 v154, v[214:217] offset:8192
	v_mfma_f32_32x32x16_bf16 v[16:31], v[150:153], v[238:241], v[16:31]
	v_add_u32_e32 v150, s16, v173
	s_waitcnt vmcnt(2)
	ds_write_b128 v150, v[218:221] offset:49152
	s_waitcnt vmcnt(1)
	ds_write_b128 v150, v[222:225] offset:49280
	s_waitcnt vmcnt(0)
	ds_write_b128 v150, v[226:229] offset:49408
	v_mfma_f32_32x32x16_bf16 v[16:31], v[146:149], v[242:245], v[16:31]
	s_cbranch_vccz .LBB0_2547
	s_and_saveexec_b64 s[10:11], s[6:7]
	ds_write_b32 v166, v180 offset:128
	s_or_b64 exec, exec, s[10:11]
	s_waitcnt lgkmcnt(0)
	v_add_u32_e32 v158, v165, v162
	ds_read_b128 v[146:149], v158 offset:224
	ds_read_b128 v[150:153], v158 offset:192
	ds_read_b128 v[154:157], v158 offset:160
	ds_read_b128 v[158:161], v158 offset:128
	s_waitcnt lgkmcnt(3)
	v_pk_mul_f32 v[12:13], v[12:13], v[146:147]
	s_waitcnt lgkmcnt(2)
	v_pk_mul_f32 v[8:9], v[8:9], v[150:151]
	s_waitcnt lgkmcnt(1)
	v_pk_mul_f32 v[4:5], v[4:5], v[154:155]
	v_pk_mul_f32 v[14:15], v[14:15], v[148:149]
	v_pk_mul_f32 v[10:11], v[10:11], v[152:153]
	v_pk_mul_f32 v[6:7], v[6:7], v[156:157]
	s_waitcnt lgkmcnt(0)
	v_pk_mul_f32 v[2:3], v[2:3], v[160:161]
	v_pk_mul_f32 v[0:1], v[0:1], v[158:159]
	v_pk_mul_f32 v[60:61], v[60:61], v[146:147]
	v_pk_mul_f32 v[56:57], v[56:57], v[150:151]
	v_pk_mul_f32 v[52:53], v[52:53], v[154:155]
	v_pk_mul_f32 v[62:63], v[62:63], v[148:149]
	v_pk_mul_f32 v[58:59], v[58:59], v[152:153]
	v_pk_mul_f32 v[54:55], v[54:55], v[156:157]
	v_pk_mul_f32 v[50:51], v[50:51], v[160:161]
	v_pk_mul_f32 v[48:49], v[48:49], v[158:159]
	v_pk_mul_f32 v[44:45], v[44:45], v[146:147]
	v_pk_mul_f32 v[40:41], v[40:41], v[150:151]
	v_pk_mul_f32 v[36:37], v[36:37], v[154:155]
	v_pk_mul_f32 v[46:47], v[46:47], v[148:149]
	v_pk_mul_f32 v[42:43], v[42:43], v[152:153]
	v_pk_mul_f32 v[38:39], v[38:39], v[156:157]
	v_pk_mul_f32 v[34:35], v[34:35], v[160:161]
	v_pk_mul_f32 v[32:33], v[32:33], v[158:159]
	v_pk_mul_f32 v[28:29], v[28:29], v[146:147]
	v_pk_mul_f32 v[24:25], v[24:25], v[150:151]
	v_pk_mul_f32 v[20:21], v[20:21], v[154:155]
	v_pk_mul_f32 v[30:31], v[30:31], v[148:149]
	v_pk_mul_f32 v[26:27], v[26:27], v[152:153]
	v_pk_mul_f32 v[22:23], v[22:23], v[156:157]
	v_pk_mul_f32 v[18:19], v[18:19], v[160:161]
	v_pk_mul_f32 v[16:17], v[16:17], v[158:159]
